# DA attention: key tiles visited in rotated order starting at the query block (exact-zero tile skip now also drops far-left tiles); softmax accumulation order changes, same math
# speedup vs baseline: 1.0217x; 1.0202x over previous
; __device__ __forceinline__ int v_rd_base(int lane) { return ((lane & 3) << 3) | (((lane >> 2) & 3) << 6) | (((lane >> 4) & 1) << 5) | (((lane >> 5) & 1) << 8); }
; #define WAIT_BAR_0() asm volatile("s_waitcnt vmcnt(0) lgkmcnt(0)\n\ts_barrier" ::: "memory")
; #define WAIT_BAR_0() asm volatile("s_waitcnt vmcnt(0) lgkmcnt(0)\n\ts_barrier" ::: "memory")
; #define WAIT_BAR_0() asm volatile("s_waitcnt vmcnt(0) lgkmcnt(0)\n\ts_barrier" ::: "memory")
; #define lane mk_lane()
; __device__ __forceinline__ void attn_unit_da(const AttnUnit& U, char* lds) {
;     ...
;   const unsigned kdst = lds0 + A_OFF_K + wid * 1024, vdst = lds0 + A_OFF_V + wid * 1024;
;   const int vb0 = (int)lds0 + A_OFF_V + v_rd_base(lane);
;   const long kstep = (long)KVBLK * U.ldk, vstep = (long)KVBLK * U.ldv;
;     ...
;   f32x16 p0, p1; float mn = 0.f, al = 1.f; bf16x8 pa0, pa1, pa2, pa3; const int NT = U.NT;
;   DMA_TILE(0, 0);
;   WAIT_BAR_0();
.LBB0_1934:
	s_or_b64 exec, exec, s[6:7]
	s_lshr_b32 s2, s8, 4
	s_and_b32 s2, s2, 1
	s_lshl_b32 s25, s2, 8
	s_mul_i32 s37, s37, 0x3000000
	s_lshl_b64 s[0:1], s[0:1], 1
	s_add_u32 s0, s37, s0
	s_addc_u32 s1, 0, s1
	s_add_u32 s0, s35, s0
	s_addc_u32 s1, s42, s1
	s_and_b32 s98, s66, 0xf00
	s_mul_i32 s98, s98, 0x3000
	s_add_u32 s0, s0, s98
	s_addc_u32 s1, s1, 0
	s_mulk_i32 s68, 0x3000
	s_add_u32 s2, s44, s68
	s_addc_u32 s3, s45, 0
	s_lshl_b32 s4, s24, 1
	s_add_u32 s5, s2, s18
	s_addc_u32 s6, s3, s19
	s_add_u32 s2, s5, s4
	s_addc_u32 s3, s6, 0
	s_add_u32 s2, s2, 0x1000
	s_addc_u32 s3, s3, 0
	s_add_u32 s4, s5, 0x2000
	s_addc_u32 s5, s6, 0
	s_add_u32 s2, s2, s98
	s_addc_u32 s3, s3, 0
	s_add_u32 s4, s4, s98
	s_addc_u32 s5, s5, 0
	s_lshl_b32 s6, s70, 2
	s_waitcnt lgkmcnt(1)
	v_mov_b32_e32 v6, v226
	s_add_i32 s24, s6, 0
	v_sub_u32_e32 v0, v0, v244
	s_add_i32 s24, s24, 0x18000
	v_bfe_u32 v8, v6, 4, 5
	v_cvt_f32_i32_e32 v130, v0
	s_lshl_b32 s37, s69, 10
	v_and_b32_e32 v0, 15, v6
	s_waitcnt lgkmcnt(0)
	v_lshrrev_b32_e32 v7, 4, v6
	v_mul_u32_u24_e32 v2, 0x1800, v8
	s_cmp_lg_u32 0, -1
	v_bitop3_b32 v0, v7, v0, 7 bitop3:0x6c
	v_lshlrev_b32_e32 v2, 1, v2
	s_cselect_b32 s6, 0, 0
	v_lshl_or_b32 v0, v0, 4, v2
	s_add_i32 s37, s37, s6
	v_lshl_add_u64 v[2:3], s[2:3], 0, v[0:1]
	v_add_u32_e32 v0, 0x60000, v0
	s_add_i32 s38, s37, 0x10000
	s_mov_b32 s7, m0
	s_mov_b32 m0, s38
	s_nop 0
	global_load_lds_dwordx4 v[2:3], off
	s_mov_b32 m0, s7
	v_lshl_add_u64 v[2:3], s[2:3], 0, v[0:1]
	s_add_i32 s2, s37, 0x12000
	s_mov_b32 s3, m0
	s_mov_b32 m0, s2
	s_nop 0
	global_load_lds_dwordx4 v[2:3], off
	s_mov_b32 m0, s3
	v_and_b32_e32 v2, 0x60, v6
	v_lshlrev_b32_e32 v3, 3, v6
	v_and_or_b32 v9, v3, 24, v2
	v_lshrrev_b32_e32 v2, 1, v6
	v_lshrrev_b32_e32 v3, 5, v6
	v_bfe_u32 v0, v6, 2, 2
	v_and_b32_e32 v2, 8, v2
	v_and_b32_e32 v3, 4, v3
	v_or3_b32 v6, v3, v0, v2
	v_and_or_b32 v0, v7, 16, v6
	v_mul_u32_u24_e32 v0, 0x1800, v0
	v_or_b32_e32 v0, v0, v9
	v_or_b32_e32 v8, 32, v8
	v_lshlrev_b32_e32 v0, 1, v0
	v_lshl_add_u64 v[2:3], s[4:5], 0, v[0:1]
	v_and_or_b32 v0, v8, 48, v6
	v_mul_u32_u24_e32 v0, 0x1800, v0
	v_or_b32_e32 v0, v0, v9
	s_mov_b32 s2, m0
	s_mov_b32 m0, s37
	s_nop 0
	global_load_lds_dwordx4 v[2:3], off
	s_mov_b32 m0, s2
	v_lshl_add_u64 v[2:3], v[2:3], 0, s[22:23]
	v_lshlrev_b32_e32 v0, 1, v0
	s_add_i32 s2, s37, 0x4000
	s_mov_b32 s3, m0
	s_mov_b32 m0, s2
	s_nop 0
	global_load_lds_dwordx4 v[2:3], off
	s_mov_b32 m0, s3
	v_lshl_add_u64 v[2:3], s[4:5], 0, v[0:1]
	s_add_i32 s2, s37, 0x2000
	s_mov_b32 s3, m0
	s_mov_b32 m0, s2
	s_nop 0
	global_load_lds_dwordx4 v[2:3], off
	s_mov_b32 m0, s3
	v_lshl_add_u64 v[2:3], v[2:3], 0, s[22:23]
	s_add_i32 s2, s37, 0x6000
	s_mov_b32 s3, m0
	s_mov_b32 m0, s2
	s_nop 0
	global_load_lds_dwordx4 v[2:3], off
	s_mov_b32 m0, s3
	v_lshlrev_b32_e32 v2, 3, v243
	v_lshlrev_b32_e32 v3, 4, v243
	v_lshlrev_b32_e32 v239, 4, v5
	v_and_b32_e32 v6, 0xc0, v3
	v_and_b32_e32 v7, 0x118, v2
	v_lshlrev_b32_e32 v2, 2, v5
	v_lshlrev_b32_e32 v3, 4, v4
	v_add_u32_e32 v5, 32, v239
	v_bitop3_b32 v247, v5, v3, s60 bitop3:0x78
	v_add_u32_e32 v5, 64, v239
	v_bitop3_b32 v248, v5, v3, s60 bitop3:0x78
	v_add_u32_e32 v5, 0x60, v239
	v_bitop3_b32 v249, v5, v3, s60 bitop3:0x78
	v_add_u32_e32 v5, 0x80, v239
	v_bitop3_b32 v250, v5, v3, s60 bitop3:0x78
	v_add_u32_e32 v5, 0xa0, v239
	s_add_i32 s2, 0, 0x10000
	v_bitop3_b32 v252, v5, v3, s60 bitop3:0x78
	v_add_u32_e32 v5, 0xc0, v239
	v_lshlrev_b32_e32 v0, 1, v243
	v_bitop3_b32 v253, v5, v3, s60 bitop3:0x78
	v_add_u32_e32 v5, 0xe0, v239
	s_add_u32 s4, s54, s67
	v_bitop3_b32 v246, v3, v239, s60 bitop3:0x6c
	v_bitop3_b32 v254, v5, v3, s60 bitop3:0x78
	v_ashrrev_i32_e32 v3, 31, v2
	v_and_or_b32 v0, v0, 32, v7
	s_addc_u32 s5, s55, 0
	v_mov_b32_e32 v14, v1
	v_mov_b32_e32 v15, v1
	s_waitcnt vmcnt(0) lgkmcnt(0)
	s_barrier
; #define WAIT_BAR_0() asm volatile("s_waitcnt vmcnt(0) lgkmcnt(0)\n\ts_barrier" ::: "memory")
; #define WAIT_BAR_0() asm volatile("s_waitcnt vmcnt(0) lgkmcnt(0)\n\ts_barrier" ::: "memory")
; #define WAIT_BAR_0() asm volatile("s_waitcnt vmcnt(0) lgkmcnt(0)\n\ts_barrier" ::: "memory")
; __device__ __forceinline__ void attn_unit_da(const AttnUnit& U, char* lds) {
;     ...
;   float m_reg = -1e30f, l_reg = 0; f32x16 o[8] = {}; bf16x8 qr[ND0];
;     ...
;   f32x16 p0, p1; float mn = 0.f, al = 1.f; bf16x8 pa0, pa1, pa2, pa3; const int NT = U.NT;
;   DMA_TILE(0, 0);
;   WAIT_BAR_0();
;   for (int j = 0; j < NT; ++j) {
;     const int st = j & 1;
;     if (j + 1 < NT) DMA_TILE(j + 1, st ^ 1);
;     float rc;
;     { const int c_ = __builtin_amdgcn_readfirstlane(cls[j]); const float* ak_ = aux + j * KVBLK;
;       if (c_ < 2) { rc = (c_ == 0) ? pq * U.nsl : -pq * U.nsl;
	v_lshl_add_u32 v245, v4, 8, s2
	v_lshl_add_u32 v251, v4, 2, s24
	v_add3_u32 v237, v6, s6, v0
	v_lshl_add_u64 v[232:233], v[2:3], 2, s[4:5]
	v_mov_b32_e32 v0, v1
	v_mov_b32_e32 v2, v1
	v_mov_b32_e32 v3, v1
	v_mov_b32_e32 v4, v1
	v_mov_b32_e32 v5, v1
	v_mov_b32_e32 v6, v1
	v_mov_b32_e32 v7, v1
	v_mov_b32_e32 v8, v1
	v_mov_b32_e32 v9, v1
	v_mov_b32_e32 v10, v1
	v_mov_b32_e32 v11, v1
	v_mov_b32_e32 v12, v1
	v_mov_b32_e32 v13, v1
	v_mov_b64_e32 v[128:129], v[14:15]
	v_mov_b64_e32 v[112:113], v[14:15]
	v_mov_b64_e32 v[96:97], v[14:15]
	v_mov_b64_e32 v[80:81], v[14:15]
	v_mov_b64_e32 v[64:65], v[14:15]
	v_mov_b64_e32 v[48:49], v[14:15]
	v_mov_b64_e32 v[32:33], v[14:15]
	v_mov_b64_e32 v[126:127], v[12:13]
	v_mov_b64_e32 v[124:125], v[10:11]
	v_mov_b64_e32 v[122:123], v[8:9]
	v_mov_b64_e32 v[120:121], v[6:7]
	v_mov_b64_e32 v[118:119], v[4:5]
	v_mov_b64_e32 v[116:117], v[2:3]
	v_mov_b64_e32 v[114:115], v[0:1]
	v_mov_b64_e32 v[110:111], v[12:13]
	v_mov_b64_e32 v[108:109], v[10:11]
	v_mov_b64_e32 v[106:107], v[8:9]
	v_mov_b64_e32 v[104:105], v[6:7]
	v_mov_b64_e32 v[102:103], v[4:5]
	v_mov_b64_e32 v[100:101], v[2:3]
	v_mov_b64_e32 v[98:99], v[0:1]
	v_mov_b64_e32 v[94:95], v[12:13]
	v_mov_b64_e32 v[92:93], v[10:11]
	v_mov_b64_e32 v[90:91], v[8:9]
	v_mov_b64_e32 v[88:89], v[6:7]
	v_mov_b64_e32 v[86:87], v[4:5]
	v_mov_b64_e32 v[84:85], v[2:3]
	v_mov_b64_e32 v[82:83], v[0:1]
	v_mov_b64_e32 v[78:79], v[12:13]
	v_mov_b64_e32 v[76:77], v[10:11]
	v_mov_b64_e32 v[74:75], v[8:9]
	v_mov_b64_e32 v[72:73], v[6:7]
	v_mov_b64_e32 v[70:71], v[4:5]
	v_mov_b64_e32 v[68:69], v[2:3]
	v_mov_b64_e32 v[66:67], v[0:1]
	v_mov_b64_e32 v[62:63], v[12:13]
	v_mov_b64_e32 v[60:61], v[10:11]
	v_mov_b64_e32 v[58:59], v[8:9]
	v_mov_b64_e32 v[56:57], v[6:7]
	v_mov_b64_e32 v[54:55], v[4:5]
	v_mov_b64_e32 v[52:53], v[2:3]
	v_mov_b64_e32 v[50:51], v[0:1]
	v_mov_b64_e32 v[46:47], v[12:13]
	v_mov_b64_e32 v[44:45], v[10:11]
	v_mov_b64_e32 v[42:43], v[8:9]
	v_mov_b64_e32 v[40:41], v[6:7]
	v_mov_b64_e32 v[38:39], v[4:5]
	v_mov_b64_e32 v[36:37], v[2:3]
	v_mov_b64_e32 v[34:35], v[0:1]
	v_mov_b64_e32 v[30:31], v[12:13]
	v_mov_b64_e32 v[28:29], v[10:11]
	v_mov_b64_e32 v[26:27], v[8:9]
	v_mov_b64_e32 v[24:25], v[6:7]
	v_mov_b64_e32 v[22:23], v[4:5]
	v_mov_b64_e32 v[20:21], v[2:3]
	v_mov_b64_e32 v[18:19], v[0:1]
	v_mov_b64_e32 v[16:17], v[14:15]
	s_mov_b32 s36, 0
	v_cmp_gt_u32_e64 s[2:3], 32, v243
	v_mov_b32_e32 v230, v228
	v_mov_b32_e32 v231, v228
	v_mov_b32_e32 v131, v130
	v_mov_b32_e32 v132, v130
	v_mov_b32_e32 v133, v130
	v_mov_b32_e32 v134, v130
	v_mov_b32_e32 v135, v130
	v_mov_b32_e32 v136, v130
	v_mov_b32_e32 v137, v130
	v_mov_b32_e32 v138, v130
	v_mov_b32_e32 v139, v130
	v_mov_b32_e32 v140, v130
	v_mov_b32_e32 v141, v130
	v_mov_b32_e32 v142, v130
	v_mov_b32_e32 v240, 0
	v_mov_b32_e32 v238, 0xf149f2ca
	s_and_b32 s98, s66, 0xf00
	s_lshl_b32 s6, s98, 2
	s_mov_b32 s7, 0
	s_and_b32 s99, s66, 0xf00
	s_lshr_b32 s99, s99, 4
	s_add_i32 s39, s99, 0x1c800
	s_and_b32 s99, s66, 0xf00
	s_lshl_b32 s99, s99, 2
	v_add_u32_e32 v227, s99, v239
	v_mov_b32_e32 v143, v130
	v_mov_b32_e32 v144, v130
	v_mov_b32_e32 v145, v130
	v_mov_b64_e32 v[14:15], v[12:13]
	v_mov_b64_e32 v[12:13], v[10:11]
	v_mov_b64_e32 v[10:11], v[8:9]
	v_mov_b64_e32 v[8:9], v[6:7]
	v_mov_b64_e32 v[6:7], v[4:5]
	v_mov_b64_e32 v[4:5], v[2:3]
	v_mov_b64_e32 v[2:3], v[0:1]
	s_branch .LBB0_1938

; #define SBAR() __builtin_amdgcn_sched_barrier(0)
; __device__ __forceinline__ int crow(int r, int hi) { return (r & 3) + 8 * (r >> 2) + 4 * hi; }
; #define WAIT_BAR_0() asm volatile("s_waitcnt vmcnt(0) lgkmcnt(0)\n\ts_barrier" ::: "memory")
; #define WAIT_BAR_0() asm volatile("s_waitcnt vmcnt(0) lgkmcnt(0)\n\ts_barrier" ::: "memory")
; #define WAIT_BAR_0() asm volatile("s_waitcnt vmcnt(0) lgkmcnt(0)\n\ts_barrier" ::: "memory")
; __device__ __forceinline__ void attn_unit_da(const AttnUnit& U, char* lds) {
;     ...
;   for (int j = 0; j < NT; ++j) {
;     const int st = j & 1;
;     if (j + 1 < NT) DMA_TILE(j + 1, st ^ 1);
;     float rc;
;     { const int c_ = __builtin_amdgcn_readfirstlane(cls[j]); const float* ak_ = aux + j * KVBLK;
;       if (c_ < 2) { rc = (c_ == 0) ? pq * U.nsl : -pq * U.nsl;
; #pragma unroll
;         for (int g = 0; g < 4; ++g) { const f32x4 a_ = *(const f32x4*)(ak_ + 8 * g + 4 * hi), b_ = *(const f32x4*)(ak_ + 32 + 8 * g + 4 * hi);
; #pragma unroll
;           for (int e = 0; e < 4; ++e) { p0[4 * g + e] = a_[e]; p1[4 * g + e] = b_[e]; } } }
;       else { rc = 0.f; const int* pg_ = U.posg + j * KVBLK;
; #pragma unroll
;         for (int g = 0; g < 4; ++g)
; #pragma unroll
;           for (int e = 0; e < 4; ++e) { p0[4 * g + e] = fabsf(pq - (float)(pg_[8 * g + 4 * hi + e] - pq0i)) * U.nsl; p1[4 * g + e] = fabsf(pq - (float)(pg_[32 + 8 * g + 4 * hi + e] - pq0i)) * U.nsl; } } }
;     SBAR(); qkt_acc<DQK>(p0, p1, K_lds + st * SHM_K, qr, r32, hi); SBAR();
;     const float pmax = rowmax32(p0, p1) + rc;
;     if (!__all((pmax - m_reg) * U.C < -150.f)) {
;       partialSM_rc(p0, p1, m_reg, mn, al, U.C, U.thr, rc, pmax);
;       if (__any(al < 1.f)) { if (hi == 0) al_l[r32] = al; asm volatile("s_waitcnt lgkmcnt(0)" ::: "memory");
; #pragma unroll
;         for (int d = 0; d < 8; ++d)
; #pragma unroll
;           for (int r = 0; r < 16; ++r) o[d][r] *= al_l[crow(r, hi)]; }
;       finishSM(p0, p1, al, l_reg, pa0, pa1, pa2, pa3); SBAR();
;       pv_d0_lean(o, vb0 + st * SHM_V2, pa0, pa1, pa2, pa3); SBAR();
;       pv_d0_lean(o + 4, vb0 + st * SHM_V2 + 16384, pa0, pa1, pa2, pa3);
;     }
;     WAIT_BAR_0();
;   }
.LBB0_1937:
	s_add_u32 s6, s6, 0x100
	s_addc_u32 s7, s7, 0
	s_add_i32 s39, s39, 4
	v_add_u32_e32 v227, 0x100, v227
	s_cmpk_lg_i32 s6, 0x4000
	s_cbranch_scc1 .Lda_nowrap1
	s_mov_b32 s6, 0
	s_addk_i32 s39, 0xff00
	v_add_u32_e32 v227, 0xffffc000, v227
.Lda_nowrap1:
	s_waitcnt vmcnt(0) lgkmcnt(0)
	s_barrier
	s_add_u32 s0, s0, 0xc0000
	s_addc_u32 s1, s1, 0
	s_cmpk_lg_i32 s6, 0x3f00
	s_cbranch_scc1 .Lda_nowrap2
	s_sub_u32 s0, s0, 0x3000000
	s_subb_u32 s1, s1, 0
.Lda_nowrap2:
	s_add_i32 s36, s36, 1
	s_cmpk_eq_i32 s36, 64
	s_cbranch_scc1 .LBB0_1948

; __global__ void __launch_bounds__(512, 2) fwd_kernel(Params p) {
	.amdhsa_kernel _Z10fwd_kernel6Params
		.amdhsa_group_segment_fixed_size 0
		.amdhsa_private_segment_fixed_size 0
		.amdhsa_kernarg_size 536
		.amdhsa_user_sgpr_count 2
		.amdhsa_user_sgpr_dispatch_ptr 0
		.amdhsa_user_sgpr_queue_ptr 0
		.amdhsa_user_sgpr_kernarg_segment_ptr 1
		.amdhsa_user_sgpr_dispatch_id 0
		.amdhsa_user_sgpr_kernarg_preload_length 0
		.amdhsa_user_sgpr_kernarg_preload_offset 0
		.amdhsa_user_sgpr_private_segment_size 0
		.amdhsa_uses_dynamic_stack 0
		.amdhsa_enable_private_segment 0
		.amdhsa_system_sgpr_workgroup_id_x 1
		.amdhsa_system_sgpr_workgroup_id_y 0
		.amdhsa_system_sgpr_workgroup_id_z 0
		.amdhsa_system_sgpr_workgroup_info 0
		.amdhsa_system_vgpr_workitem_id 2
		.amdhsa_next_free_vgpr 256
		.amdhsa_next_free_sgpr 100
		.amdhsa_accum_offset 256
		.amdhsa_reserve_vcc 1
		.amdhsa_float_round_mode_32 0
		.amdhsa_float_round_mode_16_64 0
		.amdhsa_float_denorm_mode_32 3
		.amdhsa_float_denorm_mode_16_64 3
		.amdhsa_dx10_clamp 1
		.amdhsa_ieee_mode 1
		.amdhsa_fp16_overflow 0
		.amdhsa_tg_split 0
		.amdhsa_exception_fp_ieee_invalid_op 0
		.amdhsa_exception_fp_denorm_src 0
		.amdhsa_exception_fp_ieee_div_zero 0
		.amdhsa_exception_fp_ieee_overflow 0
		.amdhsa_exception_fp_ieee_underflow 0
		.amdhsa_exception_fp_ieee_inexact 0
		.amdhsa_exception_int_div_zero 0
	.end_amdhsa_kernel

; __global__ void __launch_bounds__(512, 2) fwd_kernel(Params p) {
amdhsa.kernels:
  - .agpr_count:     0
    .args:
      - .offset:         0
        .size:           280
        .value_kind:     by_value
      - .offset:         280
        .size:           4
        .value_kind:     hidden_block_count_x
      - .offset:         284
        .size:           4
        .value_kind:     hidden_block_count_y
      - .offset:         288
        .size:           4
        .value_kind:     hidden_block_count_z
      - .offset:         292
        .size:           2
        .value_kind:     hidden_group_size_x
      - .offset:         294
        .size:           2
        .value_kind:     hidden_group_size_y
      - .offset:         296
        .size:           2
        .value_kind:     hidden_group_size_z
      - .offset:         298
        .size:           2
        .value_kind:     hidden_remainder_x
      - .offset:         300
        .size:           2
        .value_kind:     hidden_remainder_y
      - .offset:         302
        .size:           2
        .value_kind:     hidden_remainder_z
      - .offset:         320
        .size:           8
        .value_kind:     hidden_global_offset_x
      - .offset:         328
        .size:           8
        .value_kind:     hidden_global_offset_y
      - .offset:         336
        .size:           8
        .value_kind:     hidden_global_offset_z
      - .offset:         344
        .size:           2
        .value_kind:     hidden_grid_dims
      - .offset:         368
        .size:           8
        .value_kind:     hidden_multigrid_sync_arg
      - .offset:         400
        .size:           4
        .value_kind:     hidden_dynamic_lds_size
    .group_segment_fixed_size: 0
    .kernarg_segment_align: 8
    .kernarg_segment_size: 536
    .language:       OpenCL C
    .language_version:
      - 2
      - 0
    .max_flat_workgroup_size: 512
    .name:           _Z10fwd_kernel6Params
    .private_segment_fixed_size: 0
    .sgpr_count:     106
    .sgpr_spill_count: 61
    .symbol:         _Z10fwd_kernel6Params.kd
    .uniform_work_group_size: 1
    .uses_dynamic_stack: false
    .vgpr_count:     256
    .vgpr_spill_count: 0
    .wavefront_size: 64
